# v43 plus nt on the conv phase's once-read Z row loads and the final LayerNorm's Y loads
# speedup vs baseline: 1.0101x; 1.0049x over previous
; __device__ __forceinline__ void ln_phase(const float* __restrict__ Y, const float* __restrict__ g, const float* __restrict__ b, float* __restrict__ outF, int G, const int tid_in) {
;     ...
;     for (int m = gw; m < T; m += NGW) {
;         const f32x4* yr = (const f32x4*)(Y + (size_t)m * D) + lane;
;         f32x4 v[8]; float s = 0.f;
; #pragma unroll
;         for (int j = 0; j < 8; ++j) { v[j] = yr[64 * j]; s += (v[j].x + v[j].y) + (v[j].z + v[j].w); }
;         const float mean = wave_sum(s) * (1.f / D); float s2 = 0.f;
; #pragma unroll
;         for (int j = 0; j < 8; ++j) { v[j] = v[j] - mean; s2 += (v[j].x * v[j].x + v[j].y * v[j].y) + (v[j].z * v[j].z + v[j].w * v[j].w); }
;         const float rstd = 1.f / sqrtf(wave_sum(s2) * (1.f / D) + 1e-5f);
.LBB0_82:
	v_lshl_add_u64 v[70:71], v[66:67], 0, v[84:85]
	s_mov_b32 s4, 0x1fc01000
	v_add_co_u32_e64 v98, s[36:37], s4, v70
	v_add_co_u32_e32 v82, vcc, 0x1fc00000, v70
	s_nop 0
	v_addc_co_u32_e64 v99, s[36:37], 0, v71, s[36:37]
	global_load_dwordx4 v[86:89], v[98:99], off offset:1024 nt
	global_load_dwordx4 v[90:93], v[98:99], off offset:2048 nt
	global_load_dwordx4 v[94:97], v[98:99], off offset:3072 nt
	s_nop 0
	global_load_dwordx4 v[98:101], v[98:99], off nt
	v_addc_co_u32_e32 v83, vcc, 0, v71, vcc
	global_load_dwordx4 v[102:105], v[82:83], off nt
	global_load_dwordx4 v[106:109], v[82:83], off offset:1024 nt
	global_load_dwordx4 v[110:113], v[82:83], off offset:2048 nt
	global_load_dwordx4 v[114:117], v[82:83], off offset:3072 nt
	v_add_u32_e32 v64, s50, v64
	s_movk_i32 s0, 0x1fff
	v_cmp_lt_i32_e64 s[0:1], s0, v64
	s_or_b64 s[38:39], s[0:1], s[38:39]
	v_lshl_add_u64 v[72:73], v[68:69], 0, v[84:85]
	v_lshl_add_u64 v[66:67], v[66:67], 0, s[6:7]
	v_lshl_add_u64 v[68:69], v[68:69], 0, s[6:7]
	v_add_co_u32_e64 v74, s[36:37], s17, v72
	s_waitcnt vmcnt(7)
	v_mov_b32_e32 v70, v87
	v_mov_b32_e32 v71, v88
	v_mov_b32_e32 v82, v86
	v_mov_b32_e32 v83, v89
	s_waitcnt vmcnt(6)
	v_add_f32_e32 v118, v90, v91
	v_add_f32_e32 v120, v92, v93
	s_waitcnt vmcnt(5)
	v_mov_b32_e32 v119, v96
	v_mov_b32_e32 v121, v97
	v_pk_add_f32 v[70:71], v[70:71], v[82:83]
	v_pk_add_f32 v[82:83], v[118:119], v[120:121]
	s_waitcnt vmcnt(3)
	v_mov_b32_e32 v118, v102
	s_waitcnt vmcnt(2)
	v_mov_b32_e32 v119, v106
	v_mov_b32_e32 v120, v103
	v_mov_b32_e32 v121, v107
	v_mov_b32_e32 v128, v104
	v_mov_b32_e32 v129, v108
	v_mov_b32_e32 v130, v105
	v_mov_b32_e32 v131, v109
	s_waitcnt vmcnt(1)
	v_mov_b32_e32 v132, v111
	v_mov_b32_e32 v133, v112
	v_mov_b32_e32 v134, v110
	v_mov_b32_e32 v135, v113
	v_pk_add_f32 v[118:119], v[118:119], v[120:121]
	v_pk_add_f32 v[120:121], v[128:129], v[130:131]
	v_pk_add_f32 v[128:129], v[132:133], v[134:135]
	v_pk_add_f32 v[118:119], v[118:119], v[120:121]
	v_pk_add_f32 v[120:121], v[128:129], v[128:129] op_sel:[0,1] op_sel_hi:[1,0]
	v_add_f32_e32 v65, 0, v118
	v_mov_b32_e32 v123, v100
	v_mov_b32_e32 v125, v101
	v_mov_b32_e32 v127, v98
	s_waitcnt vmcnt(0)
	v_add_f32_e32 v122, v114, v115
	v_add_f32_e32 v124, v116, v117
	v_mov_b32_e32 v121, v99
	v_add_f32_e32 v126, v65, v119
	v_pk_add_f32 v[122:123], v[122:123], v[124:125]
	v_pk_add_f32 v[118:119], v[126:127], v[120:121]
	v_pk_add_f32 v[70:71], v[70:71], v[70:71] op_sel:[0,1] op_sel_hi:[1,0]
	v_pk_add_f32 v[118:119], v[118:119], v[122:123]
	v_mov_b32_e32 v71, v95
	v_pk_add_f32 v[118:119], v[118:119], v[118:119] op_sel:[0,1] op_sel_hi:[1,0]
	v_addc_co_u32_e64 v75, s[36:37], 0, v73, s[36:37]
	v_mov_b32_e32 v119, v94
	v_pk_add_f32 v[70:71], v[118:119], v[70:71]
	s_nop 0
	v_pk_add_f32 v[70:71], v[70:71], v[82:83]
	s_nop 0
	v_add_f32_e32 v65, v70, v71
	ds_bpermute_b32 v70, v76, v65
	s_waitcnt lgkmcnt(0)
	v_add_f32_e32 v65, v65, v70
	ds_bpermute_b32 v70, v77, v65
	s_waitcnt lgkmcnt(0)
	v_add_f32_e32 v65, v65, v70
	ds_bpermute_b32 v70, v78, v65
	s_waitcnt lgkmcnt(0)
	v_add_f32_e32 v65, v65, v70
	ds_bpermute_b32 v70, v79, v65
	s_waitcnt lgkmcnt(0)
	v_add_f32_e32 v65, v65, v70
	ds_bpermute_b32 v70, v80, v65
	s_waitcnt lgkmcnt(0)
	v_add_f32_e32 v65, v65, v70
	ds_bpermute_b32 v70, v81, v65
	s_waitcnt lgkmcnt(0)
	v_add_f32_e32 v65, v65, v70
	v_fmamk_f32 v71, v65, 0xba000000, v111
	v_fmamk_f32 v70, v65, 0xba000000, v110
	v_fmamk_f32 v113, v65, 0xba000000, v113
	v_fmac_f32_e32 v112, 0xba000000, v65
	v_fmamk_f32 v83, v65, 0xba000000, v87
	v_fmamk_f32 v82, v65, 0xba000000, v86
	v_fmamk_f32 v89, v65, 0xba000000, v89
	v_fmac_f32_e32 v88, 0xba000000, v65
	v_fmamk_f32 v103, v65, 0xba000000, v103
	v_fmamk_f32 v107, v65, 0xba000000, v107
	v_fmamk_f32 v87, v65, 0xba000000, v105
	v_fmamk_f32 v105, v65, 0xba000000, v109
	v_fmac_f32_e32 v102, 0xba000000, v65
	v_fmac_f32_e32 v106, 0xba000000, v65
	v_fmamk_f32 v86, v65, 0xba000000, v104
	v_fmamk_f32 v104, v65, 0xba000000, v108
	v_fmamk_f32 v109, v65, 0xba000000, v115
	v_fmamk_f32 v108, v65, 0xba000000, v114
	v_pk_mul_f32 v[110:111], v[112:113], v[112:113]
	v_pk_mul_f32 v[114:115], v[70:71], v[70:71]
	v_pk_mul_f32 v[118:119], v[88:89], v[88:89]
	v_pk_mul_f32 v[120:121], v[82:83], v[82:83]
	v_mov_b32_e32 v124, v103
	v_mov_b32_e32 v125, v107
	v_mov_b32_e32 v128, v87
	v_mov_b32_e32 v129, v105
	v_mov_b32_e32 v122, v102
	v_mov_b32_e32 v123, v106
	v_mov_b32_e32 v126, v86
	v_mov_b32_e32 v127, v104
	v_pk_mov_b32 v[138:139], v[114:115], v[110:111] op_sel:[1,0]
	v_mov_b32_e32 v115, v111
	v_pk_mov_b32 v[110:111], v[120:121], v[118:119] op_sel:[1,0]
	v_mov_b32_e32 v121, v119
	v_pk_mul_f32 v[118:119], v[124:125], v[124:125]
	v_pk_mul_f32 v[124:125], v[128:129], v[128:129]
	v_fmac_f32_e32 v116, 0xba000000, v65
	v_pk_fma_f32 v[118:119], v[122:123], v[122:123], v[118:119]
	v_pk_fma_f32 v[122:123], v[126:127], v[126:127], v[124:125]
	v_fmamk_f32 v117, v65, 0xba000000, v117
	v_mul_f32_e32 v130, v108, v108
	v_mul_f32_e32 v132, v116, v116
	v_pk_add_f32 v[114:115], v[138:139], v[114:115]
	v_pk_add_f32 v[118:119], v[118:119], v[122:123]
	v_fmamk_f32 v99, v65, 0xba000000, v99
	v_fmac_f32_e32 v98, 0xba000000, v65
	v_fmamk_f32 v101, v65, 0xba000000, v101
	v_fmamk_f32 v100, v65, 0xba000000, v100
	v_pk_fma_f32 v[128:129], v[108:109], v[108:109], v[130:131] op_sel_hi:[1,1,0]
	v_pk_fma_f32 v[130:131], v[116:117], v[116:117], v[132:133] op_sel_hi:[1,1,0]
	v_pk_add_f32 v[114:115], v[114:115], v[114:115] op_sel_hi:[0,1]
	v_pk_add_f32 v[118:119], v[118:119], v[118:119] op_sel_hi:[0,1]
	v_mul_f32_e32 v128, v98, v98
	v_mul_f32_e32 v130, v99, v99
	v_mul_f32_e32 v114, v100, v100
	v_mul_f32_e32 v118, v101, v101
	v_fmamk_f32 v90, v65, 0xba000000, v90
	v_fmac_f32_e32 v92, 0xba000000, v65
	v_pk_add_f32 v[110:111], v[110:111], v[120:121]
	v_pk_add_f32 v[120:121], v[128:129], v[130:131]
	v_pk_add_f32 v[114:115], v[114:115], v[118:119]
	v_fmamk_f32 v91, v65, 0xba000000, v91
	v_fmamk_f32 v93, v65, 0xba000000, v93
	v_mul_f32_e32 v134, v90, v90
	v_mul_f32_e32 v136, v92, v92
	v_pk_add_f32 v[114:115], v[120:121], v[114:115]
	v_fmamk_f32 v95, v65, 0xba000000, v95
	v_fmac_f32_e32 v94, 0xba000000, v65
	v_fmamk_f32 v97, v65, 0xba000000, v97
	v_fmamk_f32 v96, v65, 0xba000000, v96
	v_pk_fma_f32 v[132:133], v[90:91], v[90:91], v[134:135] op_sel_hi:[1,1,0]
	v_pk_fma_f32 v[134:135], v[92:93], v[92:93], v[136:137] op_sel_hi:[1,1,0]
	v_pk_add_f32 v[110:111], v[110:111], v[110:111] op_sel_hi:[0,1]
	v_pk_add_f32 v[114:115], v[114:115], v[114:115] op_sel_hi:[0,1]
	v_mul_f32_e32 v132, v94, v94
	v_mul_f32_e32 v134, v95, v95
	v_mul_f32_e32 v110, v96, v96
	v_mul_f32_e32 v114, v97, v97
	v_pk_add_f32 v[122:123], v[132:133], v[134:135]
	v_pk_add_f32 v[110:111], v[110:111], v[114:115]
	s_nop 0
	v_pk_add_f32 v[110:111], v[122:123], v[110:111]
	s_nop 0
	v_add_f32_e32 v65, v110, v111
	ds_bpermute_b32 v110, v76, v65
	s_waitcnt lgkmcnt(0)
; __device__ __forceinline__ void ln_phase(const float* __restrict__ Y, const float* __restrict__ g, const float* __restrict__ b, float* __restrict__ outF, int G, const int tid_in) {
;     ...
;         for (int j = 0; j < 8; ++j) { v[j] = v[j] - mean; s2 += (v[j].x * v[j].x + v[j].y * v[j].y) + (v[j].z * v[j].z + v[j].w * v[j].w); }
;         const float rstd = 1.f / sqrtf(wave_sum(s2) * (1.f / D) + 1e-5f);
;         f32x4* of = (f32x4*)(outF + (size_t)m * D) + lane;
; #pragma unroll
;         for (int j = 0; j < 8; ++j) { const f32x4 gg = ((const f32x4*)g)[lane + 64 * j], bb = ((const f32x4*)b)[lane + 64 * j];
;             const f32x4 o = v[j] * rstd * gg + bb; of[64 * j] = o; }
	v_add_f32_e32 v65, v65, v110
	ds_bpermute_b32 v110, v77, v65
	s_waitcnt lgkmcnt(0)
	v_add_f32_e32 v65, v65, v110
	ds_bpermute_b32 v110, v78, v65
	s_waitcnt lgkmcnt(0)
	v_add_f32_e32 v65, v65, v110
	ds_bpermute_b32 v110, v79, v65
	s_waitcnt lgkmcnt(0)
	v_add_f32_e32 v65, v65, v110
	ds_bpermute_b32 v110, v80, v65
	s_waitcnt lgkmcnt(0)
	v_add_f32_e32 v65, v65, v110
	ds_bpermute_b32 v110, v81, v65
	s_waitcnt lgkmcnt(0)
	v_add_f32_e32 v65, v65, v110
	v_fmamk_f32 v65, v65, 0x3a000000, v213
	v_mul_f32_e32 v110, 0x4f800000, v65
	v_cmp_gt_f32_e32 vcc, s25, v65
	s_nop 1
	v_cndmask_b32_e32 v65, v65, v110, vcc
	v_sqrt_f32_e32 v110, v65
	s_nop 0
	v_add_u32_e32 v111, -1, v110
	v_add_u32_e32 v114, 1, v110
	v_fma_f32 v115, -v111, v110, v65
	v_fma_f32 v118, -v114, v110, v65
	v_cmp_ge_f32_e64 s[0:1], 0, v115
	s_nop 1
	v_cndmask_b32_e64 v110, v110, v111, s[0:1]
	v_cmp_lt_f32_e64 s[0:1], 0, v118
	s_nop 1
	v_cndmask_b32_e64 v110, v110, v114, s[0:1]
	v_mul_f32_e32 v111, 0x37800000, v110
	v_cndmask_b32_e32 v110, v110, v111, vcc
	v_cmp_class_f32_e32 vcc, v65, v214
	s_nop 1
	v_cndmask_b32_e32 v65, v110, v65, vcc
	v_div_scale_f32 v110, s[0:1], v65, v65, 1.0
	v_rcp_f32_e32 v114, v110
	v_div_scale_f32 v111, vcc, 1.0, v65, 1.0
	v_fma_f32 v115, -v110, v114, 1.0
	v_fmac_f32_e32 v114, v115, v114
	v_mul_f32_e32 v115, v111, v114
	v_fma_f32 v118, -v110, v115, v111
	v_fmac_f32_e32 v115, v118, v114
	v_fma_f32 v110, -v110, v115, v111
	v_div_fmas_f32 v110, v110, v114, v115
	v_div_fixup_f32 v110, v110, v65, 1.0
	v_pk_mul_f32 v[102:103], v[102:103], v[110:111] op_sel_hi:[1,0]
	v_pk_mul_f32 v[86:87], v[86:87], v[110:111] op_sel_hi:[1,0]
	v_pk_mul_f32 v[106:107], v[106:107], v[110:111] op_sel_hi:[1,0]
	v_pk_mul_f32 v[104:105], v[104:105], v[110:111] op_sel_hi:[1,0]
	v_pk_mul_f32 v[112:113], v[112:113], v[110:111] op_sel_hi:[1,0]
	v_pk_mul_f32 v[114:115], v[116:117], v[110:111] op_sel_hi:[1,0]
	v_pk_mul_f32 v[116:117], v[98:99], v[110:111] op_sel_hi:[1,0]
	v_pk_mul_f32 v[118:119], v[88:89], v[110:111] op_sel_hi:[1,0]
	v_pk_mul_f32 v[120:121], v[92:93], v[110:111] op_sel_hi:[1,0]
	v_pk_mul_f32 v[122:123], v[94:95], v[110:111] op_sel_hi:[1,0]
	v_pk_mul_f32 v[70:71], v[70:71], v[110:111] op_sel_hi:[1,0]
	v_pk_mul_f32 v[98:99], v[108:109], v[110:111] op_sel_hi:[1,0]
	v_pk_mul_f32 v[108:109], v[100:101], v[110:111] op_sel_hi:[1,0]
	v_pk_mul_f32 v[82:83], v[82:83], v[110:111] op_sel_hi:[1,0]
	v_pk_mul_f32 v[124:125], v[90:91], v[110:111] op_sel_hi:[1,0]
	v_pk_mul_f32 v[126:127], v[96:97], v[110:111] op_sel_hi:[1,0]
	v_pk_fma_f32 v[88:89], v[58:59], v[86:87], v[62:63]
	v_pk_fma_f32 v[86:87], v[56:57], v[102:103], v[60:61]
	v_pk_fma_f32 v[92:93], v[2:3], v[104:105], v[6:7]
	v_pk_fma_f32 v[90:91], v[0:1], v[106:107], v[4:5]
	v_pk_fma_f32 v[96:97], v[10:11], v[112:113], v[14:15]
	v_pk_fma_f32 v[94:95], v[8:9], v[70:71], v[12:13]
	v_pk_fma_f32 v[100:101], v[18:19], v[114:115], v[22:23]
	v_pk_fma_f32 v[98:99], v[16:17], v[98:99], v[20:21]
	v_pk_fma_f32 v[104:105], v[26:27], v[108:109], v[30:31]
	v_pk_fma_f32 v[102:103], v[24:25], v[116:117], v[28:29]
	v_pk_fma_f32 v[108:109], v[34:35], v[118:119], v[38:39]
	v_pk_fma_f32 v[106:107], v[32:33], v[82:83], v[36:37]
	v_pk_fma_f32 v[112:113], v[42:43], v[120:121], v[46:47]
	v_pk_fma_f32 v[110:111], v[40:41], v[124:125], v[44:45]
	v_pk_fma_f32 v[116:117], v[50:51], v[126:127], v[54:55]
	v_pk_fma_f32 v[114:115], v[48:49], v[122:123], v[52:53]
	global_store_dwordx4 v[72:73], v[86:89], off
	global_store_dwordx4 v[72:73], v[90:93], off offset:1024
	global_store_dwordx4 v[72:73], v[94:97], off offset:2048
	global_store_dwordx4 v[72:73], v[98:101], off offset:3072
	global_store_dwordx4 v[74:75], v[102:105], off
	global_store_dwordx4 v[74:75], v[106:109], off offset:1024
	global_store_dwordx4 v[74:75], v[110:113], off offset:2048
	global_store_dwordx4 v[74:75], v[114:117], off offset:3072
	s_andn2_b64 exec, exec, s[38:39]
	s_cbranch_execnz .LBB0_82

; __device__ __forceinline__ void convgelu_phase(const bf16* __restrict__ Z, const float* __restrict__ cw, const float* __restrict__ cb, bf16* __restrict__ H, int G, const int tid_in) {
;     ...
;     for (int it = gid; it < (T / CG_ROWS) * (FF / 8); it += NTH) {
;         const int fc = it % (FF / 8), rb = it / (FF / 8), f = fc * 8, t0 = rb * CG_ROWS;
;         float wg[3][8], wu[3][8], bg[8], bu[8];
; #pragma unroll
;         for (int k = 0; k < 3; ++k) { const f32x4 a0 = *(const f32x4*)(cw + k * FF2 + f), a1 = *(const f32x4*)(cw + k * FF2 + f + 4), c0 = *(const f32x4*)(cw + k * FF2 + FF + f), c1 = *(const f32x4*)(cw + k * FF2 + FF + f + 4);
; #pragma unroll
;             for (int e = 0; e < 4; ++e) { wg[k][e] = a0[e]; wg[k][4 + e] = a1[e]; wu[k][e] = c0[e]; wu[k][4 + e] = c1[e]; } }
;         { const f32x4 a0 = *(const f32x4*)(cb + f), a1 = *(const f32x4*)(cb + f + 4), c0 = *(const f32x4*)(cb + FF + f), c1 = *(const f32x4*)(cb + FF + f + 4);
; #pragma unroll
;           for (int e = 0; e < 4; ++e) { bg[e] = a0[e]; bg[4 + e] = a1[e]; bu[e] = c0[e]; bu[4 + e] = c1[e]; } }
;         v4u g2 = {0, 0, 0, 0}, g1 = {0, 0, 0, 0}, u2 = {0, 0, 0, 0}, u1 = {0, 0, 0, 0};
;         const bf16* zp = Z + (size_t)t0 * FF2 + f;
;         if ((t0 & (SEQ - 1)) != 0) { g2 = *(const v4u*)(zp - 2 * (size_t)FF2); g1 = *(const v4u*)(zp - (size_t)FF2); u2 = *(const v4u*)(zp - 2 * (size_t)FF2 + FF); u1 = *(const v4u*)(zp - (size_t)FF2 + FF); }
.LBB0_99:
	s_mov_b32 s4, 0x2e8ba2e9
	v_mul_hi_i32 v0, v138, s4
	v_lshrrev_b32_e32 v1, 31, v0
	v_ashrrev_i32_e32 v0, 7, v0
	v_add_u32_e32 v69, v0, v1
	v_mul_i32_i24_e32 v0, 0x2c0, v69
	v_sub_u32_e32 v0, v138, v0
	v_lshlrev_b32_e32 v64, 3, v0
	s_waitcnt lgkmcnt(1)
	v_ashrrev_i32_e32 v65, 31, v64
	v_lshlrev_b64 v[56:57], 2, v[64:65]
	v_lshl_add_u64 v[4:5], s[38:39], 0, v[56:57]
	v_lshl_add_u64 v[12:13], s[44:45], 0, v[56:57]
	v_lshl_add_u64 v[20:21], s[46:47], 0, v[56:57]
	v_lshl_add_u64 v[28:29], s[48:49], 0, v[56:57]
	v_lshl_add_u64 v[36:37], s[50:51], 0, v[56:57]
	v_lshl_add_u64 v[44:45], s[54:55], 0, v[56:57]
	v_lshl_add_u64 v[52:53], s[40:41], 0, v[56:57]
	v_lshl_add_u64 v[60:61], s[42:43], 0, v[56:57]
	s_waitcnt lgkmcnt(0)
	global_load_dwordx4 v[0:3], v[4:5], off offset:16
	s_nop 0
	global_load_dwordx4 v[4:7], v[4:5], off
	s_nop 0
	global_load_dwordx4 v[8:11], v[12:13], off offset:16
	s_nop 0
	global_load_dwordx4 v[12:15], v[12:13], off
	s_nop 0
	global_load_dwordx4 v[16:19], v[20:21], off offset:16
	s_nop 0
	global_load_dwordx4 v[20:23], v[20:21], off
	s_nop 0
	global_load_dwordx4 v[24:27], v[28:29], off offset:16
	s_nop 0
	global_load_dwordx4 v[28:31], v[28:29], off
	s_nop 0
	global_load_dwordx4 v[32:35], v[36:37], off offset:16
	s_nop 0
	global_load_dwordx4 v[36:39], v[36:37], off
	s_nop 0
	global_load_dwordx4 v[40:43], v[44:45], off offset:16
	s_nop 0
	global_load_dwordx4 v[44:47], v[44:45], off
	s_nop 0
	global_load_dwordx4 v[48:51], v[52:53], off offset:16
	s_nop 0
	global_load_dwordx4 v[52:55], v[52:53], off
	s_nop 0
	global_load_dwordx4 v[56:59], v[60:61], off offset:16
	s_nop 0
	global_load_dwordx4 v[60:63], v[60:61], off
	v_mov_b32_e32 v84, v85
	v_mov_b32_e32 v86, v85
	v_mov_b32_e32 v87, v85
	v_mov_b64_e32 v[96:97], v[86:87]
	v_mov_b64_e32 v[92:93], v[86:87]
	v_mov_b64_e32 v[80:81], v[84:85]
	v_lshlrev_b32_e32 v68, 4, v69
	s_movk_i32 s4, 0x5800
	v_and_b32_e32 v69, 0x7f, v69
	v_mov_b64_e32 v[94:95], v[84:85]
	v_mov_b64_e32 v[90:91], v[84:85]
	v_mov_b64_e32 v[82:83], v[86:87]
	v_mov_b64_e32 v[88:89], v[86:87]
	v_mad_i64_i32 v[66:67], s[4:5], v68, s4, 0
	v_cmp_ne_u32_e32 vcc, 0, v69
	v_mov_b64_e32 v[86:87], v[84:85]
	s_and_saveexec_b64 s[30:31], vcc
	s_cbranch_execz .LBB0_101
	v_readlane_b32 s4, v252, 8
	v_readlane_b32 s5, v252, 9
	s_nop 1
	v_lshl_add_u64 v[70:71], s[4:5], 0, v[66:67]
	v_lshl_add_u64 v[70:71], v[64:65], 1, v[70:71]
	v_add_co_u32_e32 v72, vcc, 0xffff5000, v70
	s_nop 1
	v_addc_co_u32_e32 v73, vcc, -1, v71, vcc
	v_add_co_u32_e32 v74, vcc, 0xffffb000, v70
	s_nop 1
	v_addc_co_u32_e32 v75, vcc, -1, v71, vcc
	global_load_dwordx4 v[86:89], v[72:73], off nt
	global_load_dwordx4 v[80:83], v[74:75], off offset:-2048 nt
	v_add_co_u32_e32 v72, vcc, 0xffff8000, v70
	s_nop 1
	v_addc_co_u32_e32 v73, vcc, -1, v71, vcc
	v_add_co_u32_e32 v70, vcc, 0xffffe000, v70
	s_nop 1
	v_addc_co_u32_e32 v71, vcc, -1, v71, vcc
	global_load_dwordx4 v[90:93], v[72:73], off offset:-1024 nt
	global_load_dwordx4 v[94:97], v[70:71], off offset:-3072 nt

; __device__ __forceinline__ unsigned cvtpk(float lo, float hi) { return pg8::cvt_pk_bf16(lo, hi); }
; __device__ __forceinline__ float bflo(unsigned w) { return __uint_as_float(w << 16); }
; __device__ __forceinline__ float bfhi(unsigned w) { return __uint_as_float(w & 0xffff0000u); }
; __device__ __forceinline__ float gelu_tanh(float x) { const float y = x * (1.0f + 0.044715f * x * x); return x * rcp(1.0f + ex2(-2.0f * 0.7978845608028654f * LOG2E * y)); }
; __device__ __forceinline__ void convgelu_phase(const bf16* __restrict__ Z, const float* __restrict__ cw, const float* __restrict__ cb, bf16* __restrict__ H, int G, const int tid_in) {
;     ...
;         for (int n4 = 0; n4 < CG_ROWS; n4 += 4) {
;             v4u gq[4], uq[4];
; #pragma unroll
;             for (int i = 0; i < 4; ++i) { gq[i] = *(const v4u*)(zp + (size_t)(n4 + i) * FF2); uq[i] = *(const v4u*)(zp + (size_t)(n4 + i) * FF2 + FF); }
; #pragma unroll
;             for (int i = 0; i < 4; ++i) { const v4u g0 = gq[i], u0 = uq[i];
;                 float o[8];
; #pragma unroll
;                 for (int e = 0; e < 4; ++e) {
;                     const float ga = bg[2 * e] + wg[0][2 * e] * bflo(g2[e]) + wg[1][2 * e] * bflo(g1[e]) + wg[2][2 * e] * bflo(g0[e]);
;                     const float gb = bg[2 * e + 1] + wg[0][2 * e + 1] * bfhi(g2[e]) + wg[1][2 * e + 1] * bfhi(g1[e]) + wg[2][2 * e + 1] * bfhi(g0[e]);
;                     const float ua = bu[2 * e] + wu[0][2 * e] * bflo(u2[e]) + wu[1][2 * e] * bflo(u1[e]) + wu[2][2 * e] * bflo(u0[e]);
;                     const float ub = bu[2 * e + 1] + wu[0][2 * e + 1] * bfhi(u2[e]) + wu[1][2 * e + 1] * bfhi(u1[e]) + wu[2][2 * e + 1] * bfhi(u0[e]);
;                     o[2 * e] = gelu_tanh(ga) * ua; o[2 * e + 1] = gelu_tanh(gb) * ub;
;                 }
;                 v4u w; w.x = cvtpk(o[0], o[1]); w.y = cvtpk(o[2], o[3]); w.z = cvtpk(o[4], o[5]); w.w = cvtpk(o[6], o[7]);
;                 *(v4u*)(hp + (size_t)(n4 + i) * FF) = w;
.LBB0_102:
	v_lshl_add_u64 v[64:65], v[118:119], 0, v[114:115]
	v_add_co_u32_e32 v66, vcc, 0x2cc00000, v64
	s_waitcnt vmcnt(3)
	v_lshlrev_b32_e32 v120, 16, v86
	v_addc_co_u32_e32 v67, vcc, 0, v65, vcc
	global_load_dwordx4 v[110:113], v[66:67], off nt
	v_add_co_u32_e32 v66, vcc, 0x2cc02000, v64
	v_and_b32_e32 v121, 0xffff0000, v86
	s_nop 0
	v_addc_co_u32_e32 v67, vcc, 0, v65, vcc
	global_load_dwordx4 v[106:109], v[66:67], off offset:3072 nt
	s_waitcnt vmcnt(4)
	v_pk_fma_f32 v[120:121], v[4:5], v[120:121], v[52:53]
	v_lshlrev_b32_e32 v124, 16, v80
	v_and_b32_e32 v125, 0xffff0000, v80
	v_pk_fma_f32 v[122:123], v[20:21], v[124:125], v[120:121]
	v_add_co_u32_e32 v66, vcc, 0x2cc05000, v64
	s_waitcnt vmcnt(2)
	v_lshlrev_b32_e32 v126, 16, v94
	v_addc_co_u32_e32 v67, vcc, 0, v65, vcc
	v_and_b32_e32 v127, 0xffff0000, v94
	global_load_dwordx4 v[102:105], v[66:67], off offset:2048 nt
	v_lshlrev_b32_e32 v86, 16, v87
	v_and_b32_e32 v87, 0xffff0000, v87
	v_pk_fma_f32 v[86:87], v[6:7], v[86:87], v[54:55]
	v_add_co_u32_e32 v66, vcc, 0x2cc08000, v64
	v_lshlrev_b32_e32 v134, 16, v82
	s_nop 0
	v_addc_co_u32_e32 v67, vcc, 0, v65, vcc
	global_load_dwordx4 v[98:101], v[66:67], off offset:1024 nt
	v_and_b32_e32 v135, 0xffff0000, v82
	v_lshlrev_b32_e32 v144, 16, v83
	v_and_b32_e32 v145, 0xffff0000, v83
	v_lshlrev_b32_e32 v136, 16, v96
	v_and_b32_e32 v137, 0xffff0000, v96
	v_add_co_u32_e32 v66, vcc, 0x2cc0b000, v64
	v_lshlrev_b32_e32 v146, 16, v97
	s_nop 0
	v_addc_co_u32_e32 v67, vcc, 0, v65, vcc
	v_and_b32_e32 v147, 0xffff0000, v97
	global_load_dwordx4 v[72:75], v[66:67], off nt
	v_add_co_u32_e32 v66, vcc, 0x2cc0d000, v64
	s_mov_b32 s4, 0x37c00000
	s_nop 0
	v_addc_co_u32_e32 v67, vcc, 0, v65, vcc
	global_load_dwordx4 v[68:71], v[66:67], off offset:3072 nt
	v_add_co_u32_e32 v66, vcc, 0x2cc10000, v64
	s_add_i32 s28, s28, 4
	s_nop 0
	v_addc_co_u32_e32 v67, vcc, 0, v65, vcc
	v_add_co_u32_e32 v64, vcc, 0x2cc13000, v64
	global_load_dwordx4 v[76:79], v[66:67], off offset:2048 nt
	s_nop 0
	v_addc_co_u32_e32 v65, vcc, 0, v65, vcc
	global_load_dwordx4 v[64:67], v[64:65], off offset:1024 nt
	s_cmp_gt_u32 s28, 11
	s_waitcnt vmcnt(7)
	v_lshlrev_b32_e32 v120, 16, v110
	v_and_b32_e32 v121, 0xffff0000, v110
	v_pk_fma_f32 v[128:129], v[36:37], v[120:121], v[122:123]
	v_lshlrev_b32_e32 v122, 16, v90
	v_mul_f32_e32 v80, 0x3d372713, v128
	v_fma_f32 v80, v128, v80, 1.0
	v_mul_f32_e32 v80, v128, v80
	v_mul_f32_e32 v80, 0xc0135761, v80
	v_exp_f32_e32 v80, v80
	v_and_b32_e32 v123, 0xffff0000, v90
	v_pk_fma_f32 v[122:123], v[12:13], v[122:123], v[60:61]
	v_lshlrev_b32_e32 v110, 16, v95
	v_add_f32_e32 v80, 1.0, v80
	v_rcp_f32_e32 v132, v80
	v_mul_f32_e32 v80, 0x3d372713, v129
	v_fma_f32 v80, v129, v80, 1.0
	v_mul_f32_e32 v80, v129, v80
	v_mul_f32_e32 v80, 0xc0135761, v80
	v_exp_f32_e32 v80, v80
	v_pk_fma_f32 v[130:131], v[28:29], v[126:127], v[122:123]
	s_waitcnt vmcnt(6)
	v_lshlrev_b32_e32 v122, 16, v106
	v_and_b32_e32 v123, 0xffff0000, v106
	v_add_f32_e32 v80, 1.0, v80
	v_rcp_f32_e32 v133, v80
	v_pk_fma_f32 v[130:131], v[44:45], v[122:123], v[130:131]
	v_lshlrev_b32_e32 v80, 16, v111
	v_pk_mul_f32 v[128:129], v[128:129], v[132:133]
	s_nop 0
	v_pk_mul_f32 v[130:131], v[130:131], v[128:129]
	v_lshlrev_b32_e32 v128, 16, v81
	v_and_b32_e32 v129, 0xffff0000, v81
	v_pk_fma_f32 v[86:87], v[22:23], v[128:129], v[86:87]
	v_and_b32_e32 v81, 0xffff0000, v111
	v_pk_fma_f32 v[132:133], v[38:39], v[80:81], v[86:87]
	v_and_b32_e32 v111, 0xffff0000, v95
	v_mul_f32_e32 v84, 0x3d372713, v132
	v_fma_f32 v84, v132, v84, 1.0
	v_mul_f32_e32 v84, v132, v84
	v_mul_f32_e32 v84, 0xc0135761, v84
	v_exp_f32_e32 v84, v84
	v_lshlrev_b32_e32 v86, 16, v91
	v_and_b32_e32 v87, 0xffff0000, v91
	v_pk_fma_f32 v[86:87], v[14:15], v[86:87], v[62:63]
	v_add_f32_e32 v84, 1.0, v84
	v_rcp_f32_e32 v94, v84
	v_mul_f32_e32 v84, 0x3d372713, v133
	v_fma_f32 v84, v133, v84, 1.0
	v_mul_f32_e32 v84, v133, v84
	v_mul_f32_e32 v84, 0xc0135761, v84
	v_exp_f32_e32 v84, v84
	v_pk_fma_f32 v[90:91], v[30:31], v[110:111], v[86:87]
	v_lshlrev_b32_e32 v86, 16, v107
	v_and_b32_e32 v87, 0xffff0000, v107
	v_add_f32_e32 v84, 1.0, v84
	v_rcp_f32_e32 v95, v84
	v_pk_fma_f32 v[90:91], v[46:47], v[86:87], v[90:91]
	v_pk_mul_f32 v[94:95], v[132:133], v[94:95]
	s_nop 0
	v_pk_mul_f32 v[106:107], v[90:91], v[94:95]
	v_lshlrev_b32_e32 v90, 16, v88
	v_and_b32_e32 v91, 0xffff0000, v88
	v_pk_fma_f32 v[90:91], v[0:1], v[90:91], v[48:49]
	v_lshlrev_b32_e32 v88, 16, v89
	v_pk_fma_f32 v[94:95], v[16:17], v[134:135], v[90:91]
	v_lshlrev_b32_e32 v90, 16, v112
	v_and_b32_e32 v91, 0xffff0000, v112
	v_pk_fma_f32 v[132:133], v[32:33], v[90:91], v[94:95]
	v_and_b32_e32 v89, 0xffff0000, v89
	v_mul_f32_e32 v82, 0x3d372713, v132
	v_fma_f32 v82, v132, v82, 1.0
	v_mul_f32_e32 v82, v132, v82
	v_mul_f32_e32 v82, 0xc0135761, v82
	v_exp_f32_e32 v82, v82
	v_pk_fma_f32 v[88:89], v[2:3], v[88:89], v[50:51]
	v_lshlrev_b32_e32 v94, 16, v92
	v_and_b32_e32 v95, 0xffff0000, v92
	v_add_f32_e32 v82, 1.0, v82
	v_rcp_f32_e32 v142, v82
	v_mul_f32_e32 v82, 0x3d372713, v133
	v_fma_f32 v82, v133, v82, 1.0
	v_mul_f32_e32 v82, v133, v82
	v_mul_f32_e32 v82, 0xc0135761, v82
	v_exp_f32_e32 v82, v82
	v_pk_fma_f32 v[94:95], v[8:9], v[94:95], v[56:57]
	v_lshlrev_b32_e32 v92, 16, v93
	v_pk_fma_f32 v[140:141], v[24:25], v[136:137], v[94:95]
	v_add_f32_e32 v82, 1.0, v82
	v_rcp_f32_e32 v143, v82
	v_pk_fma_f32 v[82:83], v[18:19], v[144:145], v[88:89]
	v_lshlrev_b32_e32 v88, 16, v113
	v_and_b32_e32 v89, 0xffff0000, v113
	v_pk_fma_f32 v[82:83], v[34:35], v[88:89], v[82:83]
	v_lshlrev_b32_e32 v94, 16, v108
	v_mul_f32_e32 v84, 0x3d372713, v82
	v_fma_f32 v84, v82, v84, 1.0
	v_mul_f32_e32 v84, v82, v84
	v_mul_f32_e32 v84, 0xc0135761, v84
	v_exp_f32_e32 v84, v84
	v_and_b32_e32 v95, 0xffff0000, v108
	v_and_b32_e32 v93, 0xffff0000, v93
	v_pk_fma_f32 v[140:141], v[40:41], v[94:95], v[140:141]
	v_add_f32_e32 v84, 1.0, v84
	v_rcp_f32_e32 v96, v84
	v_mul_f32_e32 v84, 0x3d372713, v83
	v_fma_f32 v84, v83, v84, 1.0
	v_mul_f32_e32 v84, v83, v84
	v_mul_f32_e32 v84, 0xc0135761, v84
	v_exp_f32_e32 v84, v84
	v_pk_mul_f32 v[132:133], v[132:133], v[142:143]
	v_pk_fma_f32 v[92:93], v[10:11], v[92:93], v[58:59]
	v_pk_mul_f32 v[142:143], v[140:141], v[132:133]
	v_add_f32_e32 v84, 1.0, v84
	v_rcp_f32_e32 v97, v84
	v_pk_fma_f32 v[92:93], v[26:27], v[146:147], v[92:93]
	v_lshlrev_b32_e32 v132, 16, v109
	v_and_b32_e32 v133, 0xffff0000, v109
	v_pk_fma_f32 v[92:93], v[42:43], v[132:133], v[92:93]
	v_pk_mul_f32 v[82:83], v[82:83], v[96:97]
	v_cvt_pk_bf16_f32 v142, v142, v143
	v_pk_mul_f32 v[82:83], v[92:93], v[82:83]
	v_cvt_pk_bf16_f32 v140, v130, v131
	v_cvt_pk_bf16_f32 v143, v82, v83
	v_lshl_add_u64 v[82:83], v[116:117], 0, v[114:115]
	v_add_co_u32_e32 v92, vcc, s4, v82
	v_cvt_pk_bf16_f32 v141, v106, v107
	s_nop 0
	v_addc_co_u32_e32 v93, vcc, 0, v83, vcc
	global_store_dwordx4 v[92:93], v[140:143], off
	v_pk_fma_f32 v[92:93], v[4:5], v[124:125], v[52:53]
	s_waitcnt vmcnt(6)
; __device__ __forceinline__ unsigned cvtpk(float lo, float hi) { return pg8::cvt_pk_bf16(lo, hi); }
; __device__ __forceinline__ float bflo(unsigned w) { return __uint_as_float(w << 16); }
; __device__ __forceinline__ float bfhi(unsigned w) { return __uint_as_float(w & 0xffff0000u); }
; __device__ __forceinline__ float gelu_tanh(float x) { const float y = x * (1.0f + 0.044715f * x * x); return x * rcp(1.0f + ex2(-2.0f * 0.7978845608028654f * LOG2E * y)); }
; __device__ __forceinline__ void convgelu_phase(const bf16* __restrict__ Z, const float* __restrict__ cw, const float* __restrict__ cb, bf16* __restrict__ H, int G, const int tid_in) {
;     ...
;             for (int i = 0; i < 4; ++i) { const v4u g0 = gq[i], u0 = uq[i];
;                 float o[8];
; #pragma unroll
;                 for (int e = 0; e < 4; ++e) {
;                     const float ga = bg[2 * e] + wg[0][2 * e] * bflo(g2[e]) + wg[1][2 * e] * bflo(g1[e]) + wg[2][2 * e] * bflo(g0[e]);
;                     const float gb = bg[2 * e + 1] + wg[0][2 * e + 1] * bfhi(g2[e]) + wg[1][2 * e + 1] * bfhi(g1[e]) + wg[2][2 * e + 1] * bfhi(g0[e]);
;                     const float ua = bu[2 * e] + wu[0][2 * e] * bflo(u2[e]) + wu[1][2 * e] * bflo(u1[e]) + wu[2][2 * e] * bflo(u0[e]);
;                     const float ub = bu[2 * e + 1] + wu[0][2 * e + 1] * bfhi(u2[e]) + wu[1][2 * e + 1] * bfhi(u1[e]) + wu[2][2 * e + 1] * bfhi(u0[e]);
;                     o[2 * e] = gelu_tanh(ga) * ua; o[2 * e + 1] = gelu_tanh(gb) * ub;
;                 }
;                 v4u w; w.x = cvtpk(o[0], o[1]); w.y = cvtpk(o[2], o[3]); w.z = cvtpk(o[4], o[5]); w.w = cvtpk(o[6], o[7]);
;                 *(v4u*)(hp + (size_t)(n4 + i) * FF) = w;
	v_lshlrev_b32_e32 v124, 16, v102
	v_pk_fma_f32 v[92:93], v[20:21], v[120:121], v[92:93]
	v_and_b32_e32 v125, 0xffff0000, v102
	v_pk_fma_f32 v[92:93], v[36:37], v[124:125], v[92:93]
	v_pk_fma_f32 v[96:97], v[12:13], v[126:127], v[60:61]
	v_mul_f32_e32 v84, 0x3d372713, v92
	v_fma_f32 v84, v92, v84, 1.0
	v_mul_f32_e32 v84, v92, v84
	v_mul_f32_e32 v84, 0xc0135761, v84
	v_exp_f32_e32 v84, v84
	v_pk_fma_f32 v[96:97], v[28:29], v[122:123], v[96:97]
	s_waitcnt vmcnt(5)
	v_lshlrev_b32_e32 v112, 16, v98
	v_and_b32_e32 v113, 0xffff0000, v98
	v_add_f32_e32 v84, 1.0, v84
	v_rcp_f32_e32 v106, v84
	v_mul_f32_e32 v84, 0x3d372713, v93
	v_fma_f32 v84, v93, v84, 1.0
	v_mul_f32_e32 v84, v93, v84
	v_mul_f32_e32 v84, 0xc0135761, v84
	v_exp_f32_e32 v84, v84
	v_pk_fma_f32 v[96:97], v[44:45], v[112:113], v[96:97]
	v_lshlrev_b32_e32 v108, 16, v103
	v_and_b32_e32 v109, 0xffff0000, v103
	v_add_f32_e32 v84, 1.0, v84
	v_rcp_f32_e32 v107, v84
	v_lshlrev_b32_e32 v102, 16, v104
	v_and_b32_e32 v103, 0xffff0000, v104
	s_mov_b32 s4, 0x37c02000
	v_pk_mul_f32 v[92:93], v[92:93], v[106:107]
	v_lshlrev_b32_e32 v106, 16, v99
	v_pk_mul_f32 v[126:127], v[96:97], v[92:93]
	v_pk_fma_f32 v[92:93], v[6:7], v[128:129], v[54:55]
	v_and_b32_e32 v107, 0xffff0000, v99
	v_pk_fma_f32 v[92:93], v[22:23], v[80:81], v[92:93]
	v_pk_fma_f32 v[96:97], v[14:15], v[110:111], v[62:63]
	v_pk_fma_f32 v[92:93], v[38:39], v[108:109], v[92:93]
	v_pk_fma_f32 v[96:97], v[30:31], v[86:87], v[96:97]
	v_mul_f32_e32 v84, 0x3d372713, v92
	v_fma_f32 v84, v92, v84, 1.0
	v_mul_f32_e32 v84, v92, v84
	v_mul_f32_e32 v84, 0xc0135761, v84
	v_exp_f32_e32 v84, v84
	v_pk_fma_f32 v[96:97], v[46:47], v[106:107], v[96:97]
	v_cvt_pk_bf16_f32 v126, v126, v127
	v_pk_fma_f32 v[80:81], v[6:7], v[80:81], v[54:55]
	v_add_f32_e32 v84, 1.0, v84
	v_rcp_f32_e32 v98, v84
	v_mul_f32_e32 v84, 0x3d372713, v93
	v_fma_f32 v84, v93, v84, 1.0
	v_mul_f32_e32 v84, v93, v84
	v_mul_f32_e32 v84, 0xc0135761, v84
	v_exp_f32_e32 v84, v84
	v_pk_fma_f32 v[80:81], v[22:23], v[108:109], v[80:81]
	v_pk_fma_f32 v[86:87], v[14:15], v[86:87], v[62:63]
	v_add_f32_e32 v84, 1.0, v84
	v_rcp_f32_e32 v99, v84
	v_pk_fma_f32 v[86:87], v[30:31], v[106:107], v[86:87]
	v_pk_mul_f32 v[92:93], v[92:93], v[98:99]
	s_nop 0
	v_pk_mul_f32 v[110:111], v[96:97], v[92:93]
	v_pk_fma_f32 v[92:93], v[0:1], v[134:135], v[48:49]
	v_pk_fma_f32 v[96:97], v[8:9], v[136:137], v[56:57]
	v_pk_fma_f32 v[92:93], v[16:17], v[90:91], v[92:93]
	v_pk_fma_f32 v[96:97], v[24:25], v[94:95], v[96:97]
	v_pk_fma_f32 v[92:93], v[32:33], v[102:103], v[92:93]
	v_lshlrev_b32_e32 v98, 16, v100
	v_mul_f32_e32 v84, 0x3d372713, v92
	v_fma_f32 v84, v92, v84, 1.0
	v_mul_f32_e32 v84, v92, v84
	v_mul_f32_e32 v84, 0xc0135761, v84
	v_exp_f32_e32 v84, v84
	v_and_b32_e32 v99, 0xffff0000, v100
	v_pk_fma_f32 v[96:97], v[40:41], v[98:99], v[96:97]
	v_cvt_pk_bf16_f32 v127, v110, v111
	v_add_f32_e32 v84, 1.0, v84
	v_rcp_f32_e32 v128, v84
	v_mul_f32_e32 v84, 0x3d372713, v93
	v_fma_f32 v84, v93, v84, 1.0
	v_mul_f32_e32 v84, v93, v84
	v_mul_f32_e32 v84, 0xc0135761, v84
	v_exp_f32_e32 v84, v84
	v_pk_fma_f32 v[110:111], v[12:13], v[122:123], v[60:61]
	v_pk_fma_f32 v[94:95], v[8:9], v[94:95], v[56:57]
	v_pk_fma_f32 v[110:111], v[28:29], v[112:113], v[110:111]
	v_add_f32_e32 v84, 1.0, v84
	v_rcp_f32_e32 v129, v84
	v_pk_fma_f32 v[94:95], v[24:25], v[98:99], v[94:95]
	v_pk_mul_f32 v[92:93], v[92:93], v[128:129]
	s_nop 0
	v_pk_mul_f32 v[128:129], v[96:97], v[92:93]
	v_pk_fma_f32 v[92:93], v[2:3], v[144:145], v[50:51]
	v_lshlrev_b32_e32 v96, 16, v105
	v_pk_fma_f32 v[92:93], v[18:19], v[88:89], v[92:93]
	v_and_b32_e32 v97, 0xffff0000, v105
	v_pk_fma_f32 v[104:105], v[34:35], v[96:97], v[92:93]
	v_pk_fma_f32 v[92:93], v[10:11], v[146:147], v[58:59]
	v_mul_f32_e32 v84, 0x3d372713, v104
	v_fma_f32 v84, v104, v84, 1.0
	v_mul_f32_e32 v84, v104, v84
	v_mul_f32_e32 v84, 0xc0135761, v84
	v_exp_f32_e32 v84, v84
	v_pk_fma_f32 v[130:131], v[26:27], v[132:133], v[92:93]
	v_lshlrev_b32_e32 v92, 16, v101
	v_and_b32_e32 v93, 0xffff0000, v101
	v_add_f32_e32 v84, 1.0, v84
	v_pk_fma_f32 v[100:101], v[42:43], v[92:93], v[130:131]
	v_rcp_f32_e32 v130, v84
	v_mul_f32_e32 v84, 0x3d372713, v105
	v_fma_f32 v84, v105, v84, 1.0
	v_mul_f32_e32 v84, v105, v84
	v_mul_f32_e32 v84, 0xc0135761, v84
	v_exp_f32_e32 v84, v84
	v_cvt_pk_bf16_f32 v128, v128, v129
	v_add_f32_e32 v84, 1.0, v84
	v_rcp_f32_e32 v131, v84
	s_nop 0
	v_pk_mul_f32 v[104:105], v[104:105], v[130:131]
	s_nop 0
	v_pk_mul_f32 v[100:101], v[100:101], v[104:105]
	s_waitcnt vmcnt(4)
	v_lshlrev_b32_e32 v104, 16, v72
	v_cvt_pk_bf16_f32 v129, v100, v101
	v_add_co_u32_e32 v100, vcc, s4, v82
	v_and_b32_e32 v105, 0xffff0000, v72
	s_nop 0
	v_addc_co_u32_e32 v101, vcc, 0, v83, vcc
	global_store_dwordx4 v[100:101], v[126:129], off offset:3072
	v_pk_fma_f32 v[100:101], v[4:5], v[120:121], v[52:53]
	s_waitcnt vmcnt(4)
; __device__ __forceinline__ unsigned cvtpk(float lo, float hi) { return pg8::cvt_pk_bf16(lo, hi); }
; __device__ __forceinline__ float bflo(unsigned w) { return __uint_as_float(w << 16); }
; __device__ __forceinline__ float bfhi(unsigned w) { return __uint_as_float(w & 0xffff0000u); }
; __device__ __forceinline__ float gelu_tanh(float x) { const float y = x * (1.0f + 0.044715f * x * x); return x * rcp(1.0f + ex2(-2.0f * 0.7978845608028654f * LOG2E * y)); }
; __device__ __forceinline__ void convgelu_phase(const bf16* __restrict__ Z, const float* __restrict__ cw, const float* __restrict__ cb, bf16* __restrict__ H, int G, const int tid_in) {
;     ...
;             for (int i = 0; i < 4; ++i) { const v4u g0 = gq[i], u0 = uq[i];
;                 float o[8];
; #pragma unroll
;                 for (int e = 0; e < 4; ++e) {
;                     const float ga = bg[2 * e] + wg[0][2 * e] * bflo(g2[e]) + wg[1][2 * e] * bflo(g1[e]) + wg[2][2 * e] * bflo(g0[e]);
;                     const float gb = bg[2 * e + 1] + wg[0][2 * e + 1] * bfhi(g2[e]) + wg[1][2 * e + 1] * bfhi(g1[e]) + wg[2][2 * e + 1] * bfhi(g0[e]);
;                     const float ua = bu[2 * e] + wu[0][2 * e] * bflo(u2[e]) + wu[1][2 * e] * bflo(u1[e]) + wu[2][2 * e] * bflo(u0[e]);
;                     const float ub = bu[2 * e + 1] + wu[0][2 * e + 1] * bfhi(u2[e]) + wu[1][2 * e + 1] * bfhi(u1[e]) + wu[2][2 * e + 1] * bfhi(u0[e]);
;                     o[2 * e] = gelu_tanh(ga) * ua; o[2 * e + 1] = gelu_tanh(gb) * ub;
;                 }
;                 v4u w; w.x = cvtpk(o[0], o[1]); w.y = cvtpk(o[2], o[3]); w.z = cvtpk(o[4], o[5]); w.w = cvtpk(o[6], o[7]);
;                 *(v4u*)(hp + (size_t)(n4 + i) * FF) = w;
	v_lshlrev_b32_e32 v120, 16, v68
	v_pk_fma_f32 v[100:101], v[20:21], v[124:125], v[100:101]
	v_and_b32_e32 v121, 0xffff0000, v68
	v_pk_fma_f32 v[100:101], v[36:37], v[104:105], v[100:101]
	v_pk_fma_f32 v[110:111], v[44:45], v[120:121], v[110:111]
	v_mul_f32_e32 v84, 0x3d372713, v100
	v_fma_f32 v84, v100, v84, 1.0
	v_mul_f32_e32 v84, v100, v84
	v_mul_f32_e32 v84, 0xc0135761, v84
	v_exp_f32_e32 v84, v84
	v_lshlrev_b32_e32 v130, 16, v71
	v_and_b32_e32 v131, 0xffff0000, v71
	s_mov_b32 s4, 0x37c05000
	v_add_f32_e32 v84, 1.0, v84
	v_rcp_f32_e32 v122, v84
	v_mul_f32_e32 v84, 0x3d372713, v101
	v_fma_f32 v84, v101, v84, 1.0
	v_mul_f32_e32 v84, v101, v84
	v_mul_f32_e32 v84, 0xc0135761, v84
	v_exp_f32_e32 v84, v84
	s_nop 0
	v_add_f32_e32 v84, 1.0, v84
	v_rcp_f32_e32 v123, v84
	s_nop 0
	v_pk_mul_f32 v[100:101], v[100:101], v[122:123]
	s_nop 0
	v_pk_mul_f32 v[100:101], v[110:111], v[100:101]
	v_lshlrev_b32_e32 v110, 16, v73
	v_and_b32_e32 v111, 0xffff0000, v73
	v_pk_fma_f32 v[80:81], v[38:39], v[110:111], v[80:81]
	v_lshlrev_b32_e32 v122, 16, v69
	v_mul_f32_e32 v84, 0x3d372713, v80
	v_fma_f32 v84, v80, v84, 1.0
	v_mul_f32_e32 v84, v80, v84
	v_mul_f32_e32 v84, 0xc0135761, v84
	v_exp_f32_e32 v84, v84
	v_and_b32_e32 v123, 0xffff0000, v69
	v_pk_fma_f32 v[86:87], v[46:47], v[122:123], v[86:87]
	v_add_f32_e32 v84, 1.0, v84
	v_rcp_f32_e32 v126, v84
	v_mul_f32_e32 v84, 0x3d372713, v81
	v_fma_f32 v84, v81, v84, 1.0
	v_mul_f32_e32 v84, v81, v84
	v_mul_f32_e32 v84, 0xc0135761, v84
	v_exp_f32_e32 v84, v84
	s_nop 0
	v_add_f32_e32 v84, 1.0, v84
	v_rcp_f32_e32 v127, v84
	s_nop 0
	v_pk_mul_f32 v[80:81], v[80:81], v[126:127]
	s_nop 0
	v_pk_mul_f32 v[80:81], v[86:87], v[80:81]
	v_pk_fma_f32 v[86:87], v[0:1], v[90:91], v[48:49]
	v_lshlrev_b32_e32 v90, 16, v74
	v_pk_fma_f32 v[86:87], v[16:17], v[102:103], v[86:87]
	v_and_b32_e32 v91, 0xffff0000, v74
	v_pk_fma_f32 v[86:87], v[32:33], v[90:91], v[86:87]
	v_lshlrev_b32_e32 v126, 16, v70
	v_mul_f32_e32 v84, 0x3d372713, v86
	v_fma_f32 v84, v86, v84, 1.0
	v_mul_f32_e32 v84, v86, v84
	v_mul_f32_e32 v84, 0xc0135761, v84
	v_exp_f32_e32 v84, v84
	v_and_b32_e32 v127, 0xffff0000, v70
	v_pk_fma_f32 v[94:95], v[40:41], v[126:127], v[94:95]
	v_add_f32_e32 v84, 1.0, v84
	v_rcp_f32_e32 v128, v84
	v_mul_f32_e32 v84, 0x3d372713, v87
	v_fma_f32 v84, v87, v84, 1.0
	v_mul_f32_e32 v84, v87, v84
	v_mul_f32_e32 v84, 0xc0135761, v84
	v_exp_f32_e32 v84, v84
	s_nop 0
	v_add_f32_e32 v84, 1.0, v84
	v_rcp_f32_e32 v129, v84
	s_nop 0
	v_pk_mul_f32 v[86:87], v[86:87], v[128:129]
	s_nop 0
	v_pk_mul_f32 v[94:95], v[94:95], v[86:87]
	v_pk_fma_f32 v[86:87], v[2:3], v[88:89], v[50:51]
	v_lshlrev_b32_e32 v128, 16, v75
	v_pk_fma_f32 v[86:87], v[18:19], v[96:97], v[86:87]
	v_and_b32_e32 v129, 0xffff0000, v75
	v_pk_fma_f32 v[86:87], v[34:35], v[128:129], v[86:87]
	v_pk_fma_f32 v[88:89], v[10:11], v[132:133], v[58:59]
	v_mul_f32_e32 v84, 0x3d372713, v86
	v_fma_f32 v84, v86, v84, 1.0
	v_mul_f32_e32 v84, v86, v84
	v_mul_f32_e32 v84, 0xc0135761, v84
	v_exp_f32_e32 v84, v84
	v_pk_fma_f32 v[88:89], v[26:27], v[92:93], v[88:89]
	v_pk_fma_f32 v[92:93], v[10:11], v[92:93], v[58:59]
	v_pk_fma_f32 v[88:89], v[42:43], v[130:131], v[88:89]
	v_add_f32_e32 v84, 1.0, v84
	v_rcp_f32_e32 v132, v84
	v_mul_f32_e32 v84, 0x3d372713, v87
	v_fma_f32 v84, v87, v84, 1.0
	v_mul_f32_e32 v84, v87, v84
	v_mul_f32_e32 v84, 0xc0135761, v84
	v_exp_f32_e32 v84, v84
	v_pk_fma_f32 v[92:93], v[26:27], v[130:131], v[92:93]
	v_add_f32_e32 v84, 1.0, v84
	v_rcp_f32_e32 v133, v84
	s_nop 0
	v_pk_mul_f32 v[86:87], v[86:87], v[132:133]
	s_nop 0
	v_pk_mul_f32 v[132:133], v[88:89], v[86:87]
	v_cvt_pk_bf16_f32 v87, v80, v81
	v_add_co_u32_e32 v80, vcc, s4, v82
	v_cvt_pk_bf16_f32 v86, v100, v101
	v_cvt_pk_bf16_f32 v88, v94, v95
	v_cvt_pk_bf16_f32 v89, v132, v133
	v_addc_co_u32_e32 v81, vcc, 0, v83, vcc
	global_store_dwordx4 v[80:81], v[86:89], off offset:2048
	v_pk_fma_f32 v[80:81], v[4:5], v[124:125], v[52:53]
	s_waitcnt vmcnt(3)
; __device__ __forceinline__ unsigned cvtpk(float lo, float hi) { return pg8::cvt_pk_bf16(lo, hi); }
; __device__ __forceinline__ float bflo(unsigned w) { return __uint_as_float(w << 16); }
; __device__ __forceinline__ float bfhi(unsigned w) { return __uint_as_float(w & 0xffff0000u); }
; __device__ __forceinline__ float gelu_tanh(float x) { const float y = x * (1.0f + 0.044715f * x * x); return x * rcp(1.0f + ex2(-2.0f * 0.7978845608028654f * LOG2E * y)); }
; __device__ __forceinline__ void convgelu_phase(const bf16* __restrict__ Z, const float* __restrict__ cw, const float* __restrict__ cb, bf16* __restrict__ H, int G, const int tid_in) {
;     ...
;         for (int n4 = 0; n4 < CG_ROWS; n4 += 4) {
;             v4u gq[4], uq[4];
; #pragma unroll
;             for (int i = 0; i < 4; ++i) { gq[i] = *(const v4u*)(zp + (size_t)(n4 + i) * FF2); uq[i] = *(const v4u*)(zp + (size_t)(n4 + i) * FF2 + FF); }
; #pragma unroll
;             for (int i = 0; i < 4; ++i) { const v4u g0 = gq[i], u0 = uq[i];
;                 float o[8];
; #pragma unroll
;                 for (int e = 0; e < 4; ++e) {
;                     const float ga = bg[2 * e] + wg[0][2 * e] * bflo(g2[e]) + wg[1][2 * e] * bflo(g1[e]) + wg[2][2 * e] * bflo(g0[e]);
;                     const float gb = bg[2 * e + 1] + wg[0][2 * e + 1] * bfhi(g2[e]) + wg[1][2 * e + 1] * bfhi(g1[e]) + wg[2][2 * e + 1] * bfhi(g0[e]);
;                     const float ua = bu[2 * e] + wu[0][2 * e] * bflo(u2[e]) + wu[1][2 * e] * bflo(u1[e]) + wu[2][2 * e] * bflo(u0[e]);
;                     const float ub = bu[2 * e + 1] + wu[0][2 * e + 1] * bfhi(u2[e]) + wu[1][2 * e + 1] * bfhi(u1[e]) + wu[2][2 * e + 1] * bfhi(u0[e]);
;                     o[2 * e] = gelu_tanh(ga) * ua; o[2 * e + 1] = gelu_tanh(gb) * ub;
;                 }
;                 v4u w; w.x = cvtpk(o[0], o[1]); w.y = cvtpk(o[2], o[3]); w.z = cvtpk(o[4], o[5]); w.w = cvtpk(o[6], o[7]);
;                 *(v4u*)(hp + (size_t)(n4 + i) * FF) = w;
;                 g2 = g1; g1 = g0; u2 = u1; u1 = u0; }
;         }
	v_lshlrev_b32_e32 v94, 16, v65
	v_pk_fma_f32 v[80:81], v[20:21], v[104:105], v[80:81]
	v_lshlrev_b32_e32 v86, 16, v76
	v_and_b32_e32 v87, 0xffff0000, v76
	v_pk_fma_f32 v[80:81], v[36:37], v[86:87], v[80:81]
	v_pk_fma_f32 v[86:87], v[12:13], v[112:113], v[60:61]
	v_mul_f32_e32 v84, 0x3d372713, v80
	v_fma_f32 v84, v80, v84, 1.0
	v_mul_f32_e32 v84, v80, v84
	v_mul_f32_e32 v84, 0xc0135761, v84
	v_exp_f32_e32 v84, v84
	v_pk_fma_f32 v[86:87], v[28:29], v[120:121], v[86:87]
	v_lshlrev_b32_e32 v88, 16, v64
	v_and_b32_e32 v89, 0xffff0000, v64
	v_add_f32_e32 v84, 1.0, v84
	v_pk_fma_f32 v[86:87], v[44:45], v[88:89], v[86:87]
	v_rcp_f32_e32 v88, v84
	v_mul_f32_e32 v84, 0x3d372713, v81
	v_fma_f32 v84, v81, v84, 1.0
	v_mul_f32_e32 v84, v81, v84
	v_mul_f32_e32 v84, 0xc0135761, v84
	v_exp_f32_e32 v84, v84
	v_and_b32_e32 v95, 0xffff0000, v65
	s_mov_b64 s[4:5], 0xb000
	v_lshl_add_u64 v[116:117], v[116:117], 0, s[4:5]
	v_add_f32_e32 v84, 1.0, v84
	v_rcp_f32_e32 v89, v84
	s_mov_b64 s[4:5], 0x16000
	v_lshl_add_u64 v[118:119], v[118:119], 0, s[4:5]
	v_pk_mul_f32 v[80:81], v[80:81], v[88:89]
	s_nop 0
	v_pk_mul_f32 v[80:81], v[86:87], v[80:81]
	v_pk_fma_f32 v[86:87], v[6:7], v[108:109], v[54:55]
	v_lshlrev_b32_e32 v88, 16, v77
	v_pk_fma_f32 v[86:87], v[22:23], v[110:111], v[86:87]
	v_and_b32_e32 v89, 0xffff0000, v77
	v_pk_fma_f32 v[86:87], v[38:39], v[88:89], v[86:87]
	v_pk_fma_f32 v[88:89], v[14:15], v[106:107], v[62:63]
	v_mul_f32_e32 v84, 0x3d372713, v86
	v_fma_f32 v84, v86, v84, 1.0
	v_mul_f32_e32 v84, v86, v84
	v_mul_f32_e32 v84, 0xc0135761, v84
	v_exp_f32_e32 v84, v84
	v_pk_fma_f32 v[88:89], v[30:31], v[122:123], v[88:89]
	v_add_f32_e32 v84, 1.0, v84
	v_pk_fma_f32 v[88:89], v[46:47], v[94:95], v[88:89]
	v_rcp_f32_e32 v94, v84
	v_mul_f32_e32 v84, 0x3d372713, v87
	v_fma_f32 v84, v87, v84, 1.0
	v_mul_f32_e32 v84, v87, v84
	v_mul_f32_e32 v84, 0xc0135761, v84
	v_exp_f32_e32 v84, v84
	s_nop 0
	v_add_f32_e32 v84, 1.0, v84
	v_rcp_f32_e32 v95, v84
	s_nop 0
	v_pk_mul_f32 v[86:87], v[86:87], v[94:95]
	s_nop 0
	v_pk_mul_f32 v[88:89], v[88:89], v[86:87]
	v_pk_fma_f32 v[86:87], v[0:1], v[102:103], v[48:49]
	v_lshlrev_b32_e32 v94, 16, v66
	v_pk_fma_f32 v[86:87], v[16:17], v[90:91], v[86:87]
	v_lshlrev_b32_e32 v90, 16, v78
	v_and_b32_e32 v91, 0xffff0000, v78
	v_pk_fma_f32 v[86:87], v[32:33], v[90:91], v[86:87]
	v_pk_fma_f32 v[90:91], v[8:9], v[98:99], v[56:57]
	v_mul_f32_e32 v84, 0x3d372713, v86
	v_fma_f32 v84, v86, v84, 1.0
	v_mul_f32_e32 v84, v86, v84
	v_mul_f32_e32 v84, 0xc0135761, v84
	v_exp_f32_e32 v84, v84
	v_pk_fma_f32 v[90:91], v[24:25], v[126:127], v[90:91]
	v_and_b32_e32 v95, 0xffff0000, v66
	v_pk_fma_f32 v[90:91], v[40:41], v[94:95], v[90:91]
	v_add_f32_e32 v84, 1.0, v84
	v_rcp_f32_e32 v94, v84
	v_mul_f32_e32 v84, 0x3d372713, v87
	v_fma_f32 v84, v87, v84, 1.0
	v_mul_f32_e32 v84, v87, v84
	v_mul_f32_e32 v84, 0xc0135761, v84
	v_exp_f32_e32 v84, v84
	s_nop 0
	v_add_f32_e32 v84, 1.0, v84
	v_rcp_f32_e32 v95, v84
	s_nop 0
	v_pk_mul_f32 v[86:87], v[86:87], v[94:95]
	s_nop 0
	v_pk_mul_f32 v[90:91], v[90:91], v[86:87]
	v_pk_fma_f32 v[86:87], v[2:3], v[96:97], v[50:51]
	v_lshlrev_b32_e32 v94, 16, v79
	v_pk_fma_f32 v[86:87], v[18:19], v[128:129], v[86:87]
	v_and_b32_e32 v95, 0xffff0000, v79
	v_pk_fma_f32 v[86:87], v[34:35], v[94:95], v[86:87]
	v_lshlrev_b32_e32 v94, 16, v67
	v_mul_f32_e32 v84, 0x3d372713, v86
	v_fma_f32 v84, v86, v84, 1.0
	v_mul_f32_e32 v84, v86, v84
	v_mul_f32_e32 v84, 0xc0135761, v84
	v_exp_f32_e32 v84, v84
	v_and_b32_e32 v95, 0xffff0000, v67
	v_pk_fma_f32 v[92:93], v[42:43], v[94:95], v[92:93]
	v_add_f32_e32 v84, 1.0, v84
	v_rcp_f32_e32 v94, v84
	v_mul_f32_e32 v84, 0x3d372713, v87
	v_fma_f32 v84, v87, v84, 1.0
	v_mul_f32_e32 v84, v87, v84
	v_mul_f32_e32 v84, 0xc0135761, v84
	v_exp_f32_e32 v84, v84
	s_nop 0
	v_add_f32_e32 v84, 1.0, v84
	v_rcp_f32_e32 v95, v84
	s_nop 0
	v_pk_mul_f32 v[86:87], v[86:87], v[94:95]
	s_nop 0
	v_pk_mul_f32 v[92:93], v[92:93], v[86:87]
	v_cvt_pk_bf16_f32 v86, v80, v81
	v_add_co_u32_e32 v80, vcc, 0x37c08000, v82
	v_cvt_pk_bf16_f32 v87, v88, v89
	v_cvt_pk_bf16_f32 v88, v90, v91
	v_cvt_pk_bf16_f32 v89, v92, v93
	v_addc_co_u32_e32 v81, vcc, 0, v83, vcc
	global_store_dwordx4 v[80:81], v[86:89], off offset:1024
	v_mov_b64_e32 v[82:83], v[78:79]
	v_mov_b64_e32 v[92:93], v[70:71]
	v_mov_b64_e32 v[88:89], v[74:75]
	v_mov_b64_e32 v[96:97], v[66:67]
	v_mov_b64_e32 v[86:87], v[72:73]
	v_mov_b64_e32 v[80:81], v[76:77]
	v_mov_b64_e32 v[90:91], v[68:69]
	v_mov_b64_e32 v[94:95], v[64:65]
	s_cbranch_scc0 .LBB0_102
	v_readlane_b32 s4, v255, 0
	v_readlane_b32 s5, v255, 1
	s_nop 0
	v_add_u32_e32 v138, s4, v138
	s_mov_b32 s4, 0x57fff
	v_cmp_lt_i32_e32 vcc, s4, v138
	s_or_b64 s[56:57], vcc, s[56:57]
	s_andn2_b64 exec, exec, s[56:57]
	s_cbranch_execnz .LBB0_99
